# nsa-sel-direct-bias-counted-waits
# speedup vs baseline: 1.0064x; 1.0064x over previous
; #define LAS __attribute__((address_space(3)))
; __device__ __forceinline__ v16f mfma32(v8s a, v8s b, v16f c) { return __builtin_amdgcn_mfma_f32_32x32x16_bf16(a, b, c, 0, 0, 0); }
; __device__ __forceinline__ void pv_mma(const v4s (&vf)[16], const v16f& p0, const v16f& p1, v16f (&oT)[2]) {
;     v4u w[4];
;     w[0] = (v4u){pkbf(p0[0], p0[1]), pkbf(p0[2], p0[3]), pkbf(p0[4], p0[5]), pkbf(p0[6], p0[7])};
;     w[1] = (v4u){pkbf(p0[8], p0[9]), pkbf(p0[10], p0[11]), pkbf(p0[12], p0[13]), pkbf(p0[14], p0[15])};
;     w[2] = (v4u){pkbf(p1[0], p1[1]), pkbf(p1[2], p1[3]), pkbf(p1[4], p1[5]), pkbf(p1[6], p1[7])};
;     w[3] = (v4u){pkbf(p1[8], p1[9]), pkbf(p1[10], p1[11]), pkbf(p1[12], p1[13]), pkbf(p1[14], p1[15])};
; #pragma unroll
;     for (int ks = 0; ks < 4; ++ks)
; #pragma unroll
;         for (int dt = 0; dt < 2; ++dt) {
;             const v4s lo = vf[4 * ks + 2 * dt], h4 = vf[4 * ks + 2 * dt + 1];
;             const v8s af = (v8s){lo[0], lo[1], lo[2], lo[3], h4[0], h4[1], h4[2], h4[3]};
;             oT[dt] = mfma32(af, __builtin_bit_cast(v8s, w[ks]), oT[dt]);
;         }
;     __device__ __forceinline__ void apply_tab(v16f& p0, v16f& p1, int t) const {
;         const LAS float* bp = tb + (NEGPAD + qpos - 64 * t - 63 - 4 * hi);
;         v16f c0, c1;
; #pragma unroll
;         for (int r = 0; r < 16; ++r) { c0[r] = bp[63 - ((r & 3) + 8 * (r >> 2))]; c1[r] = bp[31 - ((r & 3) + 8 * (r >> 2))]; }
;         p0 = p0 * C1 + c0; p1 = p1 * C1 + c1;
;     }
.LBB0_537:
	v_cmp_neq_f32_e32 vcc, s76, v217
	s_nop 1
	v_cndmask_b32_e32 v0, 0, v217, vcc
	v_cndmask_b32_e64 v6, v0, v240, s[0:1]
	v_sub_f32_e32 v2, v73, v6
	v_sub_f32_e32 v3, v72, v6
	v_sub_f32_e32 v4, v71, v6
	v_sub_f32_e32 v5, v70, v6
	v_sub_f32_e32 v15, v69, v6
	v_sub_f32_e32 v16, v68, v6
	v_sub_f32_e32 v17, v67, v6
	v_sub_f32_e32 v18, v66, v6
	v_exp_f32_e32 v66, v18
	v_exp_f32_e32 v67, v17
	v_exp_f32_e32 v68, v16
	v_exp_f32_e32 v69, v15
	v_exp_f32_e32 v70, v5
	v_exp_f32_e32 v71, v4
	v_exp_f32_e32 v72, v3
	v_exp_f32_e32 v73, v2
	v_cvt_pk_bf16_f32 v2, v66, v67
	v_cvt_pk_bf16_f32 v3, v68, v69
	v_cvt_pk_bf16_f32 v4, v70, v71
	v_cvt_pk_bf16_f32 v5, v72, v73
	v_sub_f32_e32 v7, v81, v6
	v_sub_f32_e32 v8, v80, v6
	s_waitcnt lgkmcnt(2)
	v_mfma_f32_32x32x16_bf16 v[34:49], v[182:185], v[2:5], v[34:49]
	v_sub_f32_e32 v9, v79, v6
	v_sub_f32_e32 v10, v78, v6
	v_sub_f32_e32 v11, v77, v6
	v_sub_f32_e32 v12, v76, v6
	v_sub_f32_e32 v13, v75, v6
	v_sub_f32_e32 v14, v74, v6
	v_exp_f32_e32 v74, v14
	v_mfma_f32_32x32x16_bf16 v[50:65], v[178:181], v[2:5], v[50:65]
	v_exp_f32_e32 v75, v13
	v_exp_f32_e32 v76, v12
	v_exp_f32_e32 v77, v11
	v_exp_f32_e32 v78, v10
	v_exp_f32_e32 v79, v9
	v_exp_f32_e32 v80, v8
	v_exp_f32_e32 v81, v7
	v_cvt_pk_bf16_f32 v2, v74, v75
	v_cvt_pk_bf16_f32 v3, v76, v77
	v_cvt_pk_bf16_f32 v4, v78, v79
	v_cvt_pk_bf16_f32 v5, v80, v81
	v_sub_f32_e32 v26, v89, v6
	v_sub_f32_e32 v27, v88, v6
	v_mfma_f32_32x32x16_bf16 v[34:49], v[174:177], v[2:5], v[34:49]
	v_sub_f32_e32 v28, v87, v6
	v_sub_f32_e32 v29, v86, v6
	v_sub_f32_e32 v15, v85, v6
	v_sub_f32_e32 v16, v84, v6
	v_sub_f32_e32 v7, v83, v6
	v_sub_f32_e32 v8, v82, v6
	v_exp_f32_e32 v82, v8
	v_mfma_f32_32x32x16_bf16 v[50:65], v[170:173], v[2:5], v[50:65]
	v_exp_f32_e32 v83, v7
	v_exp_f32_e32 v84, v16
	v_exp_f32_e32 v85, v15
	v_exp_f32_e32 v86, v29
	v_exp_f32_e32 v87, v28
	v_exp_f32_e32 v88, v27
	v_exp_f32_e32 v89, v26
	v_cvt_pk_bf16_f32 v2, v82, v83
	v_cvt_pk_bf16_f32 v3, v84, v85
	v_cvt_pk_bf16_f32 v4, v86, v87
	v_cvt_pk_bf16_f32 v5, v88, v89
	v_sub_f32_e32 v19, v97, v6
	v_sub_f32_e32 v20, v96, v6
	v_mfma_f32_32x32x16_bf16 v[34:49], v[166:169], v[2:5], v[34:49]
	v_sub_f32_e32 v21, v95, v6
	v_sub_f32_e32 v22, v94, v6
	v_sub_f32_e32 v23, v93, v6
	v_sub_f32_e32 v24, v92, v6
	v_sub_f32_e32 v25, v91, v6
	v_sub_f32_e32 v6, v90, v6
	v_exp_f32_e32 v90, v6
	v_mfma_f32_32x32x16_bf16 v[50:65], v[162:165], v[2:5], v[50:65]
	v_exp_f32_e32 v91, v25
	v_exp_f32_e32 v92, v24
	v_exp_f32_e32 v93, v23
	v_exp_f32_e32 v94, v22
	v_exp_f32_e32 v95, v21
	v_exp_f32_e32 v96, v20
	v_exp_f32_e32 v97, v19
	s_nop 3
	v_cvt_pk_bf16_f32 v162, v90, v91
	v_cvt_pk_bf16_f32 v163, v92, v93
	v_cvt_pk_bf16_f32 v164, v94, v95
	v_cvt_pk_bf16_f32 v165, v96, v97
	s_nop 1
	v_mfma_f32_32x32x16_bf16 v[34:49], v[158:161], v[162:165], v[34:49]
	s_andn2_b64 vcc, exec, s[24:25]
	s_waitcnt lgkmcnt(0)
	v_mfma_f32_32x32x16_bf16 v[50:65], v[154:157], v[162:165], v[50:65]
	s_cbranch_vccnz .LBB0_543
	s_lshl_b32 s24, s50, 6
	s_sub_i32 s0, s49, s24
	s_cmpk_lt_i32 s0, 0x400
	s_mov_b64 s[0:1], -1
	s_cbranch_scc0 .LBB0_540
	v_add_u32_e32 v2, s24, v200
	v_sub_u32_e32 v2, v199, v2
	v_lshl_add_u32 v18, v2, 2, s37
	v_add_u32_e32 v18, 0xd110, v18
	ds_read2_b32 v[2:3], v18 offset0:58 offset1:59
	ds_read2_b32 v[154:155], v18 offset0:26 offset1:27
	ds_read2_b32 v[4:5], v18 offset0:56 offset1:57
	ds_read2_b32 v[20:21], v18 offset0:24 offset1:25
	ds_read2_b32 v[6:7], v18 offset0:50 offset1:51
	ds_read2_b32 v[22:23], v18 offset0:18 offset1:19
	ds_read2_b32 v[8:9], v18 offset0:48 offset1:49
	ds_read2_b32 v[24:25], v18 offset0:16 offset1:17
	ds_read2_b32 v[10:11], v18 offset0:42 offset1:43
	ds_read2_b32 v[26:27], v18 offset0:10 offset1:11
	ds_read2_b32 v[12:13], v18 offset0:40 offset1:41
	ds_read2_b32 v[28:29], v18 offset0:8 offset1:9
	ds_read2_b32 v[14:15], v18 offset0:34 offset1:35
	ds_read2_b32 v[16:17], v18 offset0:32 offset1:33
	ds_read2_b32 v[30:31], v18 offset0:0 offset1:1
	ds_read2_b32 v[32:33], v18 offset0:2 offset1:3
	s_waitcnt lgkmcnt(14)
	v_pk_fma_f32 v[114:115], v[114:115], s[52:53], v[2:3] op_sel:[0,0,1] op_sel_hi:[1,0,0]
	v_pk_fma_f32 v[98:99], v[98:99], s[52:53], v[154:155] op_sel:[0,0,1] op_sel_hi:[1,0,0]
	s_waitcnt lgkmcnt(12)
	v_pk_fma_f32 v[116:117], v[116:117], s[52:53], v[4:5] op_sel:[0,0,1] op_sel_hi:[1,0,0]
	v_pk_fma_f32 v[100:101], v[100:101], s[52:53], v[20:21] op_sel:[0,0,1] op_sel_hi:[1,0,0]
	s_waitcnt lgkmcnt(10)
	v_pk_fma_f32 v[118:119], v[118:119], s[52:53], v[6:7] op_sel:[0,0,1] op_sel_hi:[1,0,0]
	v_pk_fma_f32 v[102:103], v[102:103], s[52:53], v[22:23] op_sel:[0,0,1] op_sel_hi:[1,0,0]
	s_waitcnt lgkmcnt(8)
	v_pk_fma_f32 v[120:121], v[120:121], s[52:53], v[8:9] op_sel:[0,0,1] op_sel_hi:[1,0,0]
	v_pk_fma_f32 v[104:105], v[104:105], s[52:53], v[24:25] op_sel:[0,0,1] op_sel_hi:[1,0,0]
	s_waitcnt lgkmcnt(6)
	v_pk_fma_f32 v[122:123], v[122:123], s[52:53], v[10:11] op_sel:[0,0,1] op_sel_hi:[1,0,0]
	v_pk_fma_f32 v[106:107], v[106:107], s[52:53], v[26:27] op_sel:[0,0,1] op_sel_hi:[1,0,0]
	s_waitcnt lgkmcnt(4)
	v_pk_fma_f32 v[124:125], v[124:125], s[52:53], v[12:13] op_sel:[0,0,1] op_sel_hi:[1,0,0]
	v_pk_fma_f32 v[108:109], v[108:109], s[52:53], v[28:29] op_sel:[0,0,1] op_sel_hi:[1,0,0]
	s_waitcnt lgkmcnt(2)
	v_pk_fma_f32 v[126:127], v[126:127], s[52:53], v[14:15] op_sel:[0,0,1] op_sel_hi:[1,0,0]
	v_pk_fma_f32 v[128:129], v[128:129], s[52:53], v[16:17] op_sel:[0,0,1] op_sel_hi:[1,0,0]
	s_waitcnt lgkmcnt(0)
	v_pk_fma_f32 v[112:113], v[112:113], s[52:53], v[30:31] op_sel:[0,0,1] op_sel_hi:[1,0,0]
	v_pk_fma_f32 v[110:111], v[110:111], s[52:53], v[32:33] op_sel:[0,0,1] op_sel_hi:[1,0,0]
	s_mov_b64 s[0:1], 0
	s_branch .LBB0_543

; #define LAS __attribute__((address_space(3)))
; __device__ __forceinline__ v16f mfma32(v8s a, v8s b, v16f c) { return __builtin_amdgcn_mfma_f32_32x32x16_bf16(a, b, c, 0, 0, 0); }
; __device__ __forceinline__ void pv_mma(const v4s (&vf)[16], const v16f& p0, const v16f& p1, v16f (&oT)[2]) {
;     v4u w[4];
;     w[0] = (v4u){pkbf(p0[0], p0[1]), pkbf(p0[2], p0[3]), pkbf(p0[4], p0[5]), pkbf(p0[6], p0[7])};
;     w[1] = (v4u){pkbf(p0[8], p0[9]), pkbf(p0[10], p0[11]), pkbf(p0[12], p0[13]), pkbf(p0[14], p0[15])};
;     w[2] = (v4u){pkbf(p1[0], p1[1]), pkbf(p1[2], p1[3]), pkbf(p1[4], p1[5]), pkbf(p1[6], p1[7])};
;     w[3] = (v4u){pkbf(p1[8], p1[9]), pkbf(p1[10], p1[11]), pkbf(p1[12], p1[13]), pkbf(p1[14], p1[15])};
; #pragma unroll
;     for (int ks = 0; ks < 4; ++ks)
; #pragma unroll
;         for (int dt = 0; dt < 2; ++dt) {
;             const v4s lo = vf[4 * ks + 2 * dt], h4 = vf[4 * ks + 2 * dt + 1];
;             const v8s af = (v8s){lo[0], lo[1], lo[2], lo[3], h4[0], h4[1], h4[2], h4[3]};
;             oT[dt] = mfma32(af, __builtin_bit_cast(v8s, w[ks]), oT[dt]);
;         }
;     __device__ __forceinline__ void apply_tab(v16f& p0, v16f& p1, int t) const {
;         const LAS float* bp = tb + (NEGPAD + qpos - 64 * t - 63 - 4 * hi);
;         v16f c0, c1;
; #pragma unroll
;         for (int r = 0; r < 16; ++r) { c0[r] = bp[63 - ((r & 3) + 8 * (r >> 2))]; c1[r] = bp[31 - ((r & 3) + 8 * (r >> 2))]; }
;         p0 = p0 * C1 + c0; p1 = p1 * C1 + c1;
;     }
.LBB0_552:
	v_cndmask_b32_e64 v0, v0, v240, s[4:5]
	v_sub_f32_e32 v121, v121, v0
	v_sub_f32_e32 v120, v120, v0
	v_sub_f32_e32 v119, v119, v0
	v_sub_f32_e32 v118, v118, v0
	v_sub_f32_e32 v117, v117, v0
	v_sub_f32_e32 v116, v116, v0
	v_sub_f32_e32 v115, v115, v0
	v_sub_f32_e32 v114, v114, v0
	v_exp_f32_e32 v114, v114
	v_exp_f32_e32 v115, v115
	v_exp_f32_e32 v116, v116
	v_exp_f32_e32 v117, v117
	v_exp_f32_e32 v118, v118
	v_exp_f32_e32 v119, v119
	v_exp_f32_e32 v120, v120
	v_exp_f32_e32 v121, v121
	v_sub_f32_e32 v154, v105, v0
	v_sub_f32_e32 v155, v104, v0
	v_sub_f32_e32 v156, v103, v0
	v_sub_f32_e32 v157, v102, v0
	v_cvt_pk_bf16_f32 v102, v114, v115
	v_cvt_pk_bf16_f32 v103, v116, v117
	v_cvt_pk_bf16_f32 v104, v118, v119
	v_cvt_pk_bf16_f32 v105, v120, v121
	v_sub_f32_e32 v129, v129, v0
	v_sub_f32_e32 v128, v128, v0
	s_waitcnt lgkmcnt(2)
	v_mfma_f32_32x32x16_bf16 v[34:49], v[30:33], v[102:105], v[34:49]
	v_sub_f32_e32 v127, v127, v0
	v_sub_f32_e32 v126, v126, v0
	v_sub_f32_e32 v125, v125, v0
	v_sub_f32_e32 v124, v124, v0
	v_sub_f32_e32 v123, v123, v0
	v_sub_f32_e32 v122, v122, v0
	v_exp_f32_e32 v122, v122
	v_mfma_f32_32x32x16_bf16 v[50:65], v[26:29], v[102:105], v[50:65]
	v_exp_f32_e32 v123, v123
	v_exp_f32_e32 v124, v124
	v_exp_f32_e32 v125, v125
	v_exp_f32_e32 v126, v126
	v_exp_f32_e32 v127, v127
	v_exp_f32_e32 v128, v128
	v_exp_f32_e32 v129, v129
	v_cvt_pk_bf16_f32 v26, v122, v123
	v_cvt_pk_bf16_f32 v27, v124, v125
	v_cvt_pk_bf16_f32 v28, v126, v127
	v_cvt_pk_bf16_f32 v29, v128, v129
	v_sub_f32_e32 v30, v101, v0
	v_sub_f32_e32 v31, v100, v0
	v_mfma_f32_32x32x16_bf16 v[34:49], v[22:25], v[26:29], v[34:49]
	v_sub_f32_e32 v22, v99, v0
	v_sub_f32_e32 v23, v98, v0
	v_exp_f32_e32 v98, v23
	v_exp_f32_e32 v99, v22
	v_exp_f32_e32 v100, v31
	v_exp_f32_e32 v101, v30
	v_exp_f32_e32 v102, v157
	v_mfma_f32_32x32x16_bf16 v[50:65], v[18:21], v[26:29], v[50:65]
	v_exp_f32_e32 v103, v156
	v_exp_f32_e32 v104, v155
	v_exp_f32_e32 v105, v154
	v_cvt_pk_bf16_f32 v18, v98, v99
	v_cvt_pk_bf16_f32 v19, v100, v101
	v_cvt_pk_bf16_f32 v20, v102, v103
	v_cvt_pk_bf16_f32 v21, v104, v105
	v_sub_f32_e32 v113, v113, v0
	v_sub_f32_e32 v112, v112, v0
	v_mfma_f32_32x32x16_bf16 v[34:49], v[14:17], v[18:21], v[34:49]
	v_sub_f32_e32 v111, v111, v0
	v_sub_f32_e32 v110, v110, v0
	v_sub_f32_e32 v109, v109, v0
	v_sub_f32_e32 v108, v108, v0
	v_sub_f32_e32 v14, v107, v0
	v_sub_f32_e32 v0, v106, v0
	v_exp_f32_e32 v106, v0
	v_mfma_f32_32x32x16_bf16 v[50:65], v[10:13], v[18:21], v[50:65]
	v_exp_f32_e32 v107, v14
	v_exp_f32_e32 v108, v108
	v_exp_f32_e32 v109, v109
	v_exp_f32_e32 v110, v110
	v_exp_f32_e32 v111, v111
	v_exp_f32_e32 v112, v112
	v_exp_f32_e32 v113, v113
	v_cvt_pk_bf16_f32 v10, v106, v107
	v_cvt_pk_bf16_f32 v11, v108, v109
	v_cvt_pk_bf16_f32 v12, v110, v111
	v_cvt_pk_bf16_f32 v13, v112, v113
	s_and_b64 vcc, exec, s[0:1]
	s_nop 0
	v_mfma_f32_32x32x16_bf16 v[34:49], v[6:9], v[10:13], v[34:49]
	s_waitcnt lgkmcnt(0)
	v_mfma_f32_32x32x16_bf16 v[50:65], v[2:5], v[10:13], v[50:65]
	s_cbranch_vccnz .LBB0_558
	s_lshl_b32 s4, s26, 6
	s_sub_i32 s0, s49, s4
	s_cmpk_lt_i32 s0, 0x400
	s_mov_b64 s[0:1], -1
	s_cbranch_scc0 .LBB0_555
	v_add_u32_e32 v0, s4, v200
	v_sub_u32_e32 v0, v199, v0
	v_lshl_add_u32 v0, v0, 2, s37
	v_add_u32_e32 v0, 0xd110, v0
	ds_read2_b32 v[2:3], v0 offset0:58 offset1:59
	ds_read2_b32 v[154:155], v0 offset0:26 offset1:27
	ds_read2_b32 v[4:5], v0 offset0:56 offset1:57
	ds_read2_b32 v[20:21], v0 offset0:24 offset1:25
	ds_read2_b32 v[6:7], v0 offset0:50 offset1:51
	ds_read2_b32 v[22:23], v0 offset0:18 offset1:19
	ds_read2_b32 v[8:9], v0 offset0:48 offset1:49
	ds_read2_b32 v[24:25], v0 offset0:16 offset1:17
	ds_read2_b32 v[10:11], v0 offset0:42 offset1:43
	ds_read2_b32 v[26:27], v0 offset0:10 offset1:11
	ds_read2_b32 v[12:13], v0 offset0:40 offset1:41
	ds_read2_b32 v[28:29], v0 offset0:8 offset1:9
	ds_read2_b32 v[14:15], v0 offset0:34 offset1:35
	ds_read2_b32 v[16:17], v0 offset0:32 offset1:33
	ds_read2_b32 v[30:31], v0 offset0:0 offset1:1
	ds_read2_b32 v[32:33], v0 offset0:2 offset1:3
	s_waitcnt lgkmcnt(14)
	v_pk_fma_f32 v[66:67], v[66:67], s[52:53], v[2:3] op_sel:[0,0,1] op_sel_hi:[1,0,0]
	v_pk_fma_f32 v[82:83], v[82:83], s[52:53], v[154:155] op_sel:[0,0,1] op_sel_hi:[1,0,0]
	s_waitcnt lgkmcnt(12)
	v_pk_fma_f32 v[68:69], v[68:69], s[52:53], v[4:5] op_sel:[0,0,1] op_sel_hi:[1,0,0]
	v_pk_fma_f32 v[84:85], v[84:85], s[52:53], v[20:21] op_sel:[0,0,1] op_sel_hi:[1,0,0]
	s_waitcnt lgkmcnt(10)
	v_pk_fma_f32 v[70:71], v[70:71], s[52:53], v[6:7] op_sel:[0,0,1] op_sel_hi:[1,0,0]
	v_pk_fma_f32 v[86:87], v[86:87], s[52:53], v[22:23] op_sel:[0,0,1] op_sel_hi:[1,0,0]
	s_waitcnt lgkmcnt(8)
	v_pk_fma_f32 v[72:73], v[72:73], s[52:53], v[8:9] op_sel:[0,0,1] op_sel_hi:[1,0,0]
	v_pk_fma_f32 v[88:89], v[88:89], s[52:53], v[24:25] op_sel:[0,0,1] op_sel_hi:[1,0,0]
	s_waitcnt lgkmcnt(6)
	v_pk_fma_f32 v[74:75], v[74:75], s[52:53], v[10:11] op_sel:[0,0,1] op_sel_hi:[1,0,0]
	v_pk_fma_f32 v[90:91], v[90:91], s[52:53], v[26:27] op_sel:[0,0,1] op_sel_hi:[1,0,0]
	s_waitcnt lgkmcnt(4)
	v_pk_fma_f32 v[76:77], v[76:77], s[52:53], v[12:13] op_sel:[0,0,1] op_sel_hi:[1,0,0]
	v_pk_fma_f32 v[92:93], v[92:93], s[52:53], v[28:29] op_sel:[0,0,1] op_sel_hi:[1,0,0]
	s_waitcnt lgkmcnt(2)
	v_pk_fma_f32 v[78:79], v[78:79], s[52:53], v[14:15] op_sel:[0,0,1] op_sel_hi:[1,0,0]
	v_pk_fma_f32 v[80:81], v[80:81], s[52:53], v[16:17] op_sel:[0,0,1] op_sel_hi:[1,0,0]
	s_waitcnt lgkmcnt(0)
	v_pk_fma_f32 v[96:97], v[96:97], s[52:53], v[30:31] op_sel:[0,0,1] op_sel_hi:[1,0,0]
	v_pk_fma_f32 v[94:95], v[94:95], s[52:53], v[32:33] op_sel:[0,0,1] op_sel_hi:[1,0,0]
	s_mov_b64 s[0:1], 0
	s_branch .LBB0_558
